# GEMM: first K-iteration peeled with C=0 inline on first-touch MFMAs, removing the 128 v_mov accumulator zeroing per unit; on top of v14
# speedup vs baseline: 1.0003x; 1.0003x over previous
.LBB0_650:
	s_add_u32 s0, s0, 0x80
	s_addc_u32 s1, s1, 0
	s_add_u32 s6, s10, 0x100
	s_addc_u32 s7, s11, 0
	s_mov_b32 s10, 0
.Lgemm_peel:
	v_or_b32_e32 v0, 0x10000, v165
	v_add_u32_e32 v126, 0x10400, v165
	ds_read_b128 v[122:125], v0
	ds_read_b128 v[126:129], v126
	v_add_u32_e32 v0, 0x10800, v165
	v_add_u32_e32 v160, 0x10c00, v165
	s_add_i32 s38, s10, 2
	ds_read_b128 v[156:159], v0
	ds_read_b128 v[160:163], v160
	s_add_u32 s36, s0, 0x80
	s_addc_u32 s11, s1, 0
	s_cmp_eq_u32 s76, s10
	s_cselect_b32 s10, s92, s36
	s_cselect_b32 s11, s93, s11
	s_cselect_b32 s37, s95, s7
	s_cselect_b32 s36, s94, s6
	s_mov_b32 m0, s31
	v_lshl_add_u64 v[192:193], s[0:1], 0, v[152:153]
	ds_read_b128 v[168:171], v164
	ds_read_b128 v[172:175], v164 offset:1024
	ds_read_b128 v[176:179], v164 offset:2048
	ds_read_b128 v[180:183], v164 offset:3072
	ds_read_b128 v[184:187], v164 offset:4096
	ds_read_b128 v[188:191], v164 offset:5120
	ds_read_b128 v[206:209], v164 offset:6144
	ds_read_b128 v[210:213], v164 offset:7168
	global_load_lds_dwordx4 v[192:193], off
	v_lshl_add_u64 v[192:193], s[0:1], 0, v[154:155]
	s_mov_b32 m0, s90
	s_nop 0
	global_load_lds_dwordx4 v[192:193], off
	s_waitcnt lgkmcnt(8)
	s_barrier
	s_waitcnt lgkmcnt(0)
	s_setprio 1
	s_waitcnt lgkmcnt(0)
	v_mfma_f32_16x16x32_bf16 v[114:117], v[122:125], v[168:171], 0
	v_mfma_f32_16x16x32_bf16 v[118:121], v[156:159], v[168:171], 0
	v_mfma_f32_16x16x32_bf16 v[98:101], v[122:125], v[176:179], 0
	v_mfma_f32_16x16x32_bf16 v[102:105], v[156:159], v[176:179], 0
	v_mfma_f32_16x16x32_bf16 v[82:85], v[122:125], v[184:187], 0
	v_mfma_f32_16x16x32_bf16 v[86:89], v[156:159], v[184:187], 0
	v_mfma_f32_16x16x32_bf16 v[66:69], v[122:125], v[206:209], 0
	v_mfma_f32_16x16x32_bf16 v[70:73], v[156:159], v[206:209], 0
	v_mfma_f32_16x16x32_bf16 v[114:117], v[126:129], v[172:175], v[114:117]
	v_mfma_f32_16x16x32_bf16 v[118:121], v[160:163], v[172:175], v[118:121]
	v_mfma_f32_16x16x32_bf16 v[98:101], v[126:129], v[180:183], v[98:101]
	v_mfma_f32_16x16x32_bf16 v[102:105], v[160:163], v[180:183], v[102:105]
	v_mfma_f32_16x16x32_bf16 v[82:85], v[126:129], v[188:191], v[82:85]
	v_mfma_f32_16x16x32_bf16 v[86:89], v[160:163], v[188:191], v[86:89]
	v_mfma_f32_16x16x32_bf16 v[66:69], v[126:129], v[210:213], v[66:69]
	v_mfma_f32_16x16x32_bf16 v[70:73], v[160:163], v[210:213], v[70:73]
	s_setprio 0
	s_barrier
	v_or_b32_e32 v0, 0x14000, v165
	s_mov_b32 m0, s28
	v_add_u32_e32 v167, 0x14400, v165
	ds_read_b128 v[214:217], v0
	ds_read_b128 v[218:221], v167
	v_add_u32_e32 v0, 0x14800, v165
	v_lshl_add_u64 v[192:193], s[36:37], 0, v[140:141]
	v_add_u32_e32 v167, 0x14c00, v165
	ds_read_b128 v[222:225], v0
	ds_read_b128 v[226:229], v167
	global_load_lds_dwordx4 v[192:193], off
	v_lshl_add_u64 v[230:231], s[36:37], 0, v[150:151]
	s_mov_b32 m0, s29
	s_nop 0
	global_load_lds_dwordx4 v[230:231], off
	s_barrier
	s_waitcnt lgkmcnt(0)
	s_setprio 1
	s_waitcnt lgkmcnt(0)
	v_mfma_f32_16x16x32_bf16 v[106:109], v[214:217], v[168:171], 0
	v_mfma_f32_16x16x32_bf16 v[110:113], v[222:225], v[168:171], 0
	v_mfma_f32_16x16x32_bf16 v[90:93], v[214:217], v[176:179], 0
	v_mfma_f32_16x16x32_bf16 v[94:97], v[222:225], v[176:179], 0
	v_mfma_f32_16x16x32_bf16 v[74:77], v[214:217], v[184:187], 0
	v_mfma_f32_16x16x32_bf16 v[78:81], v[222:225], v[184:187], 0
	v_mfma_f32_16x16x32_bf16 v[58:61], v[214:217], v[206:209], 0
	v_mfma_f32_16x16x32_bf16 v[62:65], v[222:225], v[206:209], 0
	v_mfma_f32_16x16x32_bf16 v[106:109], v[218:221], v[172:175], v[106:109]
	v_mfma_f32_16x16x32_bf16 v[110:113], v[226:229], v[172:175], v[110:113]
	v_mfma_f32_16x16x32_bf16 v[90:93], v[218:221], v[180:183], v[90:93]
	v_mfma_f32_16x16x32_bf16 v[94:97], v[226:229], v[180:183], v[94:97]
	v_mfma_f32_16x16x32_bf16 v[74:77], v[218:221], v[188:191], v[74:77]
	v_mfma_f32_16x16x32_bf16 v[78:81], v[226:229], v[188:191], v[78:81]
	v_mfma_f32_16x16x32_bf16 v[58:61], v[218:221], v[210:213], v[58:61]
	v_mfma_f32_16x16x32_bf16 v[62:65], v[226:229], v[210:213], v[62:65]
	s_setprio 0
	s_mov_b32 m0, s25
	v_lshl_add_u64 v[232:233], s[10:11], 0, v[138:139]
	s_barrier
	ds_read_b128 v[168:171], v164 offset:16384
	ds_read_b128 v[172:175], v164 offset:17408
	ds_read_b128 v[176:179], v164 offset:18432
	ds_read_b128 v[180:183], v164 offset:19456
	ds_read_b128 v[184:187], v164 offset:20480
	ds_read_b128 v[188:191], v164 offset:21504
	ds_read_b128 v[206:209], v164 offset:22528
	ds_read_b128 v[210:213], v164 offset:23552
	global_load_lds_dwordx4 v[232:233], off
	v_lshl_add_u64 v[234:235], s[10:11], 0, v[148:149]
	s_mov_b32 m0, s14
	s_nop 0
	global_load_lds_dwordx4 v[234:235], off
	s_barrier
	s_waitcnt lgkmcnt(0)
	s_setprio 1
	s_waitcnt lgkmcnt(0)
	v_mfma_f32_16x16x32_bf16 v[50:53], v[122:125], v[168:171], 0
	v_mfma_f32_16x16x32_bf16 v[54:57], v[156:159], v[168:171], 0
	v_mfma_f32_16x16x32_bf16 v[34:37], v[122:125], v[176:179], 0
	v_mfma_f32_16x16x32_bf16 v[38:41], v[156:159], v[176:179], 0
	v_mfma_f32_16x16x32_bf16 v[18:21], v[122:125], v[184:187], 0
	v_mfma_f32_16x16x32_bf16 v[22:25], v[156:159], v[184:187], 0
	v_mfma_f32_16x16x32_bf16 v[2:5], v[122:125], v[206:209], 0
	v_mfma_f32_16x16x32_bf16 v[6:9], v[156:159], v[206:209], 0
	v_mfma_f32_16x16x32_bf16 v[50:53], v[126:129], v[172:175], v[50:53]
	v_mfma_f32_16x16x32_bf16 v[54:57], v[160:163], v[172:175], v[54:57]
	v_mfma_f32_16x16x32_bf16 v[34:37], v[126:129], v[180:183], v[34:37]
	v_mfma_f32_16x16x32_bf16 v[38:41], v[160:163], v[180:183], v[38:41]
	v_mfma_f32_16x16x32_bf16 v[18:21], v[126:129], v[188:191], v[18:21]
	v_mfma_f32_16x16x32_bf16 v[22:25], v[160:163], v[188:191], v[22:25]
	v_mfma_f32_16x16x32_bf16 v[2:5], v[126:129], v[210:213], v[2:5]
	v_mfma_f32_16x16x32_bf16 v[6:9], v[160:163], v[210:213], v[6:9]
	s_setprio 0
	s_barrier
	s_add_u32 s36, s36, s72
	s_addc_u32 s37, s37, 0
	s_mov_b32 m0, s15
	v_lshl_add_u64 v[236:237], s[36:37], 0, v[140:141]
	global_load_lds_dwordx4 v[236:237], off
	v_lshl_add_u64 v[238:239], s[36:37], 0, v[150:151]
	s_mov_b32 m0, s88
	s_nop 0
	global_load_lds_dwordx4 v[238:239], off
	s_waitcnt vmcnt(6)
	s_barrier
	s_setprio 1
	v_mfma_f32_16x16x32_bf16 v[42:45], v[214:217], v[168:171], 0
	v_mfma_f32_16x16x32_bf16 v[46:49], v[222:225], v[168:171], 0
	v_mfma_f32_16x16x32_bf16 v[26:29], v[214:217], v[176:179], 0
	v_mfma_f32_16x16x32_bf16 v[30:33], v[222:225], v[176:179], 0
	v_mfma_f32_16x16x32_bf16 v[10:13], v[214:217], v[184:187], 0
	v_mfma_f32_16x16x32_bf16 v[14:17], v[222:225], v[184:187], 0
	v_mfma_f32_16x16x32_bf16 v[42:45], v[218:221], v[172:175], v[42:45]
	v_mfma_f32_16x16x32_bf16 v[46:49], v[226:229], v[172:175], v[46:49]
	v_mfma_f32_16x16x32_bf16 v[26:29], v[218:221], v[180:183], v[26:29]
	v_mfma_f32_16x16x32_bf16 v[30:33], v[226:229], v[180:183], v[30:33]
	v_mfma_f32_16x16x32_bf16 v[10:13], v[218:221], v[188:191], v[10:13]
	v_mfma_f32_16x16x32_bf16 v[14:17], v[226:229], v[188:191], v[14:17]
	v_mfma_f32_16x16x32_bf16 v[122:125], v[214:217], v[206:209], 0
	v_mfma_f32_16x16x32_bf16 v[126:129], v[222:225], v[206:209], 0
	v_mfma_f32_16x16x32_bf16 v[122:125], v[218:221], v[210:213], v[122:125]
	v_mfma_f32_16x16x32_bf16 v[126:129], v[226:229], v[210:213], v[126:129]
	s_setprio 0
	v_or_b32_e32 v0, 0x18000, v165
	v_add_u32_e32 v134, 0x18400, v165
	s_barrier
	ds_read_b128 v[130:133], v0
	ds_read_b128 v[134:137], v134
	v_add_u32_e32 v0, 0x18800, v165
	v_add_u32_e32 v160, 0x18c00, v165
	ds_read_b128 v[156:159], v0
	ds_read_b128 v[160:163], v160
	s_add_u32 s10, s10, s72
	s_addc_u32 s11, s11, 0
	s_mov_b32 m0, s89
	v_lshl_add_u64 v[214:215], s[10:11], 0, v[138:139]
	ds_read_b128 v[168:171], v164 offset:32768
	ds_read_b128 v[172:175], v164 offset:33792
	ds_read_b128 v[176:179], v164 offset:34816
	ds_read_b128 v[180:183], v164 offset:35840
	ds_read_b128 v[184:187], v164 offset:36864
	ds_read_b128 v[188:191], v164 offset:37888
	ds_read_b128 v[206:209], v164 offset:38912
	ds_read_b128 v[210:213], v164 offset:39936
	global_load_lds_dwordx4 v[214:215], off
	v_lshl_add_u64 v[214:215], s[10:11], 0, v[148:149]
	s_mov_b32 m0, s60
	s_nop 0
	global_load_lds_dwordx4 v[214:215], off
	s_waitcnt lgkmcnt(8)
	s_barrier
	s_waitcnt lgkmcnt(0)
	s_setprio 1
	s_waitcnt lgkmcnt(0)
	v_mfma_f32_16x16x32_bf16 v[114:117], v[130:133], v[168:171], v[114:117]
	v_mfma_f32_16x16x32_bf16 v[118:121], v[156:159], v[168:171], v[118:121]
	v_mfma_f32_16x16x32_bf16 v[98:101], v[130:133], v[176:179], v[98:101]
	v_mfma_f32_16x16x32_bf16 v[102:105], v[156:159], v[176:179], v[102:105]
	v_mfma_f32_16x16x32_bf16 v[82:85], v[130:133], v[184:187], v[82:85]
	v_mfma_f32_16x16x32_bf16 v[86:89], v[156:159], v[184:187], v[86:89]
	v_mfma_f32_16x16x32_bf16 v[66:69], v[130:133], v[206:209], v[66:69]
	v_mfma_f32_16x16x32_bf16 v[70:73], v[156:159], v[206:209], v[70:73]
	v_mfma_f32_16x16x32_bf16 v[114:117], v[134:137], v[172:175], v[114:117]
	v_mfma_f32_16x16x32_bf16 v[118:121], v[160:163], v[172:175], v[118:121]
	v_mfma_f32_16x16x32_bf16 v[98:101], v[134:137], v[180:183], v[98:101]
	v_mfma_f32_16x16x32_bf16 v[102:105], v[160:163], v[180:183], v[102:105]
	v_mfma_f32_16x16x32_bf16 v[82:85], v[134:137], v[188:191], v[82:85]
	v_mfma_f32_16x16x32_bf16 v[86:89], v[160:163], v[188:191], v[86:89]
	v_mfma_f32_16x16x32_bf16 v[66:69], v[134:137], v[210:213], v[66:69]
	v_mfma_f32_16x16x32_bf16 v[70:73], v[160:163], v[210:213], v[70:73]
	s_setprio 0
	s_barrier
	v_or_b32_e32 v0, 0x1c000, v165
	s_mov_b32 m0, s50
	v_add_u32_e32 v167, 0x1c400, v165
	ds_read_b128 v[214:217], v0
	ds_read_b128 v[218:221], v167
	v_add_u32_e32 v0, 0x1c800, v165
	v_lshl_add_u64 v[192:193], v[192:193], 0, s[48:49]
	v_add_u32_e32 v167, 0x1cc00, v165
	ds_read_b128 v[222:225], v0
	ds_read_b128 v[226:229], v167
	global_load_lds_dwordx4 v[192:193], off
	v_lshl_add_u64 v[192:193], v[230:231], 0, s[48:49]
	s_mov_b32 m0, s51
	s_nop 0
	global_load_lds_dwordx4 v[192:193], off
	s_barrier
	s_waitcnt lgkmcnt(0)
	s_setprio 1
	s_waitcnt lgkmcnt(0)
	v_mfma_f32_16x16x32_bf16 v[106:109], v[214:217], v[168:171], v[106:109]
	v_mfma_f32_16x16x32_bf16 v[110:113], v[222:225], v[168:171], v[110:113]
	v_mfma_f32_16x16x32_bf16 v[90:93], v[214:217], v[176:179], v[90:93]
	v_mfma_f32_16x16x32_bf16 v[94:97], v[222:225], v[176:179], v[94:97]
	v_mfma_f32_16x16x32_bf16 v[74:77], v[214:217], v[184:187], v[74:77]
	v_mfma_f32_16x16x32_bf16 v[78:81], v[222:225], v[184:187], v[78:81]
	v_mfma_f32_16x16x32_bf16 v[58:61], v[214:217], v[206:209], v[58:61]
	v_mfma_f32_16x16x32_bf16 v[62:65], v[222:225], v[206:209], v[62:65]
	v_mfma_f32_16x16x32_bf16 v[106:109], v[218:221], v[172:175], v[106:109]
	v_mfma_f32_16x16x32_bf16 v[110:113], v[226:229], v[172:175], v[110:113]
	v_mfma_f32_16x16x32_bf16 v[90:93], v[218:221], v[180:183], v[90:93]
	v_mfma_f32_16x16x32_bf16 v[94:97], v[226:229], v[180:183], v[94:97]
	v_mfma_f32_16x16x32_bf16 v[74:77], v[218:221], v[188:191], v[74:77]
	v_mfma_f32_16x16x32_bf16 v[78:81], v[226:229], v[188:191], v[78:81]
	v_mfma_f32_16x16x32_bf16 v[58:61], v[218:221], v[210:213], v[58:61]
	v_mfma_f32_16x16x32_bf16 v[62:65], v[226:229], v[210:213], v[62:65]
	s_setprio 0
	s_mov_b32 m0, s52
	v_lshl_add_u64 v[192:193], v[232:233], 0, s[48:49]
	s_barrier
	ds_read_b128 v[168:171], v164 offset:49152
	ds_read_b128 v[172:175], v164 offset:50176
	ds_read_b128 v[176:179], v164 offset:51200
	ds_read_b128 v[180:183], v164 offset:52224
	ds_read_b128 v[184:187], v164 offset:53248
	ds_read_b128 v[188:191], v164 offset:54272
	ds_read_b128 v[206:209], v164 offset:55296
	ds_read_b128 v[210:213], v164 offset:56320
	global_load_lds_dwordx4 v[192:193], off
	v_lshl_add_u64 v[192:193], v[234:235], 0, s[48:49]
	s_mov_b32 m0, s53
	s_nop 0
	global_load_lds_dwordx4 v[192:193], off
	s_barrier
	s_waitcnt lgkmcnt(0)
	s_setprio 1
	s_waitcnt lgkmcnt(0)
	v_mfma_f32_16x16x32_bf16 v[50:53], v[130:133], v[168:171], v[50:53]
	v_mfma_f32_16x16x32_bf16 v[54:57], v[156:159], v[168:171], v[54:57]
	v_mfma_f32_16x16x32_bf16 v[34:37], v[130:133], v[176:179], v[34:37]
	v_mfma_f32_16x16x32_bf16 v[38:41], v[156:159], v[176:179], v[38:41]
	v_mfma_f32_16x16x32_bf16 v[18:21], v[130:133], v[184:187], v[18:21]
	v_mfma_f32_16x16x32_bf16 v[22:25], v[156:159], v[184:187], v[22:25]
	v_mfma_f32_16x16x32_bf16 v[2:5], v[130:133], v[206:209], v[2:5]
	v_mfma_f32_16x16x32_bf16 v[6:9], v[156:159], v[206:209], v[6:9]
	v_mfma_f32_16x16x32_bf16 v[50:53], v[134:137], v[172:175], v[50:53]
	v_mfma_f32_16x16x32_bf16 v[54:57], v[160:163], v[172:175], v[54:57]
	v_mfma_f32_16x16x32_bf16 v[34:37], v[134:137], v[180:183], v[34:37]
	v_mfma_f32_16x16x32_bf16 v[38:41], v[160:163], v[180:183], v[38:41]
	v_mfma_f32_16x16x32_bf16 v[18:21], v[134:137], v[188:191], v[18:21]
	v_mfma_f32_16x16x32_bf16 v[22:25], v[160:163], v[188:191], v[22:25]
	v_mfma_f32_16x16x32_bf16 v[2:5], v[134:137], v[210:213], v[2:5]
	v_mfma_f32_16x16x32_bf16 v[6:9], v[160:163], v[210:213], v[6:9]
	s_setprio 0
	s_barrier
	s_mov_b32 m0, s80
	v_lshl_add_u64 v[130:131], v[236:237], 0, s[48:49]
	global_load_lds_dwordx4 v[130:131], off
	v_lshl_add_u64 v[130:131], v[238:239], 0, s[48:49]
	s_mov_b32 m0, s58
	s_nop 0
	global_load_lds_dwordx4 v[130:131], off
	s_waitcnt vmcnt(6)
	s_barrier
	s_setprio 1
	v_mfma_f32_16x16x32_bf16 v[122:125], v[214:217], v[206:209], v[122:125]
	v_mfma_f32_16x16x32_bf16 v[42:45], v[214:217], v[168:171], v[42:45]
	v_mfma_f32_16x16x32_bf16 v[46:49], v[222:225], v[168:171], v[46:49]
	v_mfma_f32_16x16x32_bf16 v[26:29], v[214:217], v[176:179], v[26:29]
	v_mfma_f32_16x16x32_bf16 v[30:33], v[222:225], v[176:179], v[30:33]
	v_mfma_f32_16x16x32_bf16 v[10:13], v[214:217], v[184:187], v[10:13]
	v_mfma_f32_16x16x32_bf16 v[14:17], v[222:225], v[184:187], v[14:17]
	v_mfma_f32_16x16x32_bf16 v[134:137], v[218:221], v[210:213], v[122:125]
	v_mfma_f32_16x16x32_bf16 v[122:125], v[222:225], v[206:209], v[126:129]
	v_mfma_f32_16x16x32_bf16 v[42:45], v[218:221], v[172:175], v[42:45]
	v_mfma_f32_16x16x32_bf16 v[46:49], v[226:229], v[172:175], v[46:49]
	v_mfma_f32_16x16x32_bf16 v[26:29], v[218:221], v[180:183], v[26:29]
	v_mfma_f32_16x16x32_bf16 v[30:33], v[226:229], v[180:183], v[30:33]
	v_mfma_f32_16x16x32_bf16 v[10:13], v[218:221], v[188:191], v[10:13]
	v_mfma_f32_16x16x32_bf16 v[14:17], v[226:229], v[188:191], v[14:17]
	v_mfma_f32_16x16x32_bf16 v[130:133], v[226:229], v[210:213], v[122:125]
	s_setprio 0
	s_add_u32 s0, s0, 0x100
	s_addc_u32 s1, s1, 0
	s_add_u32 s6, s6, 0x100
	s_addc_u32 s7, s7, 0
	s_cmp_ge_u32 s38, s59
	s_mov_b32 s10, s38
	s_barrier
	s_cbranch_scc0 .LBB0_651
	s_branch .Lgemm_after_kloop

.Lgemm_after_kloop:
	v_mov_b32_e32 v160, v166
	s_andn2_b64 vcc, exec, s[74:75]
	v_and_b32_e32 v168, 15, v160
	v_ashrrev_i32_e32 v161, 4, v160
	s_mov_b64 s[0:1], -1
	s_cbranch_vccnz .LBB0_702
	v_cndmask_b32_e64 v0, 0, 1, s[78:79]
	v_cmp_ne_u32_e64 s[0:1], 1, v0
	s_andn2_b64 vcc, exec, s[78:79]
	s_cbranch_vccnz .LBB0_655
	v_max_f32_e32 v122, 0, v114
	v_max_f32_e32 v123, 0, v115
	v_max_f32_e32 v126, 0, v116
	v_max_f32_e32 v127, 0, v117
	v_max_f32_e32 v128, 0, v118
	v_max_f32_e32 v129, 0, v119
	v_max_f32_e32 v156, 0, v120
	v_max_f32_e32 v157, 0, v121
	v_pk_mul_f32 v[124:125], v[122:123], v[122:123]
	v_pk_mul_f32 v[126:127], v[126:127], v[126:127]
	v_pk_mul_f32 v[128:129], v[128:129], v[128:129]
	v_pk_mul_f32 v[156:157], v[156:157], v[156:157]
	s_branch .LBB0_656
